# sample-row GEMM K loops unrolled: k-step 1 weight fragments prefetched in fresh registers, row-tile pairs reloaded in place behind their last k-step-0 MFMA
# baseline (speedup 1.0000x reference)
.LBB0_141:
	v_lshl_add_u64 v[82:83], v[70:71], 0, s[0:1]
	v_add_co_u32_e32 v90, vcc, s5, v82
	v_lshl_add_u64 v[126:127], v[72:73], 0, s[0:1]
	s_nop 1
	v_addc_co_u32_e32 v91, vcc, 0, v83, vcc
	v_add_co_u32_e32 v102, vcc, s6, v82
	s_add_u32 s0, s0, 0x80
	s_nop 1
	v_addc_co_u32_e32 v103, vcc, 0, v83, vcc
	v_add_co_u32_e32 v94, vcc, s7, v126
	s_addc_u32 s1, s1, 0
	s_nop 1
	v_addc_co_u32_e32 v95, vcc, 0, v127, vcc
	v_add_co_u32_e32 v106, vcc, s8, v126
	s_cmpk_eq_i32 s0, 0x100
	s_nop 1
	v_addc_co_u32_e32 v107, vcc, 0, v127, vcc
	v_add_co_u32_e32 v110, vcc, s9, v126
	s_nop 1
	v_addc_co_u32_e32 v111, vcc, 0, v127, vcc
	v_add_co_u32_e32 v114, vcc, s10, v126
	s_nop 1
	v_addc_co_u32_e32 v115, vcc, 0, v127, vcc
	v_add_co_u32_e32 v118, vcc, s11, v126
	s_nop 1
	v_addc_co_u32_e32 v119, vcc, 0, v127, vcc
	v_add_co_u32_e32 v122, vcc, s12, v126
	s_nop 1
	v_addc_co_u32_e32 v123, vcc, 0, v127, vcc
	v_add_co_u32_e32 v128, vcc, s13, v126
	s_nop 1
	v_addc_co_u32_e32 v129, vcc, 0, v127, vcc
	v_add_co_u32_e32 v134, vcc, s14, v126
	s_nop 1
	v_addc_co_u32_e32 v135, vcc, 0, v127, vcc
	global_load_dwordx4 v[82:85], v[90:91], off
	global_load_dwordx4 v[86:89], v[94:95], off
	global_load_dwordx4 v[90:93], v[90:91], off offset:64
	global_load_dwordx4 v[94:97], v[94:95], off offset:64
	global_load_dwordx4 v[98:101], v[102:103], off
	global_load_dwordx4 v[102:105], v[102:103], off offset:64
	global_load_dwordx4 v[216:219], v[106:107], off
	global_load_dwordx4 v[106:109], v[106:107], off offset:64
	global_load_dwordx4 v[220:223], v[110:111], off
	global_load_dwordx4 v[110:113], v[110:111], off offset:64
	global_load_dwordx4 v[224:227], v[114:115], off
	global_load_dwordx4 v[114:117], v[114:115], off offset:64
	global_load_dwordx4 v[232:235], v[118:119], off
	global_load_dwordx4 v[118:121], v[118:119], off offset:64
	global_load_dwordx4 v[236:239], v[122:123], off
	global_load_dwordx4 v[122:125], v[122:123], off offset:64
	global_load_dwordx4 v[240:243], v[128:129], off
	global_load_dwordx4 v[126:129], v[128:129], off offset:64
	global_load_dwordx4 v[130:133], v[134:135], off
	global_load_dwordx4 v[244:247], v[134:135], off offset:64
	v_lshl_add_u64 v[178:179], v[70:71], 0, s[0:1]
	v_lshl_add_u64 v[180:181], v[72:73], 0, s[0:1]
	s_add_u32 s0, s0, 0x80
	s_addc_u32 s1, s1, 0
	s_cmpk_eq_i32 s0, 0x100
	v_add_co_u32_e32 v166, vcc, s5, v178
	s_nop 1
	v_addc_co_u32_e32 v167, vcc, 0, v179, vcc
	global_load_dwordx4 v[162:165], v[166:167], off
	global_load_dwordx4 v[166:169], v[166:167], off offset:64
	v_add_co_u32_e32 v174, vcc, s6, v178
	s_nop 1
	v_addc_co_u32_e32 v175, vcc, 0, v179, vcc
	global_load_dwordx4 v[170:173], v[174:175], off
	global_load_dwordx4 v[174:177], v[174:175], off offset:64
	s_waitcnt vmcnt(22)
	v_mfma_f32_16x16x32_bf16 v[56:59], v[82:85], v[86:89], v[56:59]
	s_waitcnt vmcnt(19)
	v_mfma_f32_16x16x32_bf16 v[52:55], v[98:101], v[86:89], v[52:55]
	v_mfma_f32_16x16x32_bf16 v[56:59], v[90:93], v[94:97], v[56:59]
	s_waitcnt vmcnt(18)
	v_mfma_f32_16x16x32_bf16 v[52:55], v[102:105], v[94:97], v[52:55]
	v_add_co_u32_e32 v94, vcc, s7, v180
	s_nop 1
	v_addc_co_u32_e32 v95, vcc, 0, v181, vcc
	global_load_dwordx4 v[86:89], v[94:95], off
	global_load_dwordx4 v[94:97], v[94:95], off offset:64
	s_waitcnt vmcnt(19)
	v_mfma_f32_16x16x32_bf16 v[40:43], v[82:85], v[216:219], v[40:43]
	v_mfma_f32_16x16x32_bf16 v[16:19], v[98:101], v[216:219], v[16:19]
	s_waitcnt vmcnt(18)
	v_mfma_f32_16x16x32_bf16 v[40:43], v[90:93], v[106:109], v[40:43]
	v_mfma_f32_16x16x32_bf16 v[16:19], v[102:105], v[106:109], v[16:19]
	v_add_co_u32_e32 v106, vcc, s8, v180
	s_nop 1
	v_addc_co_u32_e32 v107, vcc, 0, v181, vcc
	global_load_dwordx4 v[216:219], v[106:107], off
	global_load_dwordx4 v[106:109], v[106:107], off offset:64
	s_waitcnt vmcnt(19)
	v_mfma_f32_16x16x32_bf16 v[12:15], v[82:85], v[220:223], v[12:15]
	v_mfma_f32_16x16x32_bf16 v[8:11], v[98:101], v[220:223], v[8:11]
	s_waitcnt vmcnt(18)
	v_mfma_f32_16x16x32_bf16 v[12:15], v[90:93], v[110:113], v[12:15]
	v_mfma_f32_16x16x32_bf16 v[8:11], v[102:105], v[110:113], v[8:11]
	v_add_co_u32_e32 v110, vcc, s9, v180
	s_nop 1
	v_addc_co_u32_e32 v111, vcc, 0, v181, vcc
	global_load_dwordx4 v[220:223], v[110:111], off
	global_load_dwordx4 v[110:113], v[110:111], off offset:64
	s_waitcnt vmcnt(19)
	v_mfma_f32_16x16x32_bf16 v[4:7], v[82:85], v[224:227], v[4:7]
	v_mfma_f32_16x16x32_bf16 v[0:3], v[98:101], v[224:227], v[0:3]
	s_waitcnt vmcnt(18)
	v_mfma_f32_16x16x32_bf16 v[4:7], v[90:93], v[114:117], v[4:7]
	v_mfma_f32_16x16x32_bf16 v[0:3], v[102:105], v[114:117], v[0:3]
	v_add_co_u32_e32 v114, vcc, s10, v180
	s_nop 1
	v_addc_co_u32_e32 v115, vcc, 0, v181, vcc
	global_load_dwordx4 v[224:227], v[114:115], off
	global_load_dwordx4 v[114:117], v[114:115], off offset:64
	s_waitcnt vmcnt(19)
	v_mfma_f32_16x16x32_bf16 v[20:23], v[82:85], v[232:235], v[20:23]
	v_mfma_f32_16x16x32_bf16 v[24:27], v[98:101], v[232:235], v[24:27]
	s_waitcnt vmcnt(18)
	v_mfma_f32_16x16x32_bf16 v[20:23], v[90:93], v[118:121], v[20:23]
	v_mfma_f32_16x16x32_bf16 v[24:27], v[102:105], v[118:121], v[24:27]
	v_add_co_u32_e32 v118, vcc, s11, v180
	s_nop 1
	v_addc_co_u32_e32 v119, vcc, 0, v181, vcc
	global_load_dwordx4 v[232:235], v[118:119], off
	global_load_dwordx4 v[118:121], v[118:119], off offset:64
	s_waitcnt vmcnt(19)
	v_mfma_f32_16x16x32_bf16 v[28:31], v[82:85], v[236:239], v[28:31]
	v_mfma_f32_16x16x32_bf16 v[32:35], v[98:101], v[236:239], v[32:35]
	s_waitcnt vmcnt(18)
	v_mfma_f32_16x16x32_bf16 v[28:31], v[90:93], v[122:125], v[28:31]
	v_mfma_f32_16x16x32_bf16 v[32:35], v[102:105], v[122:125], v[32:35]
	v_add_co_u32_e32 v122, vcc, s12, v180
	s_nop 1
	v_addc_co_u32_e32 v123, vcc, 0, v181, vcc
	global_load_dwordx4 v[236:239], v[122:123], off
	global_load_dwordx4 v[122:125], v[122:123], off offset:64
	s_waitcnt vmcnt(19)
	v_mfma_f32_16x16x32_bf16 v[36:39], v[82:85], v[240:243], v[36:39]
	v_mfma_f32_16x16x32_bf16 v[44:47], v[98:101], v[240:243], v[44:47]
	s_waitcnt vmcnt(17)
	v_mfma_f32_16x16x32_bf16 v[48:51], v[82:85], v[130:133], v[48:51]
	v_mfma_f32_16x16x32_bf16 v[60:63], v[98:101], v[130:133], v[60:63]
	v_mfma_f32_16x16x32_bf16 v[36:39], v[90:93], v[126:129], v[36:39]
	v_mfma_f32_16x16x32_bf16 v[44:47], v[102:105], v[126:129], v[44:47]
	v_add_co_u32_e32 v126, vcc, s13, v180
	s_nop 1
	v_addc_co_u32_e32 v127, vcc, 0, v181, vcc
	global_load_dwordx4 v[240:243], v[126:127], off
	global_load_dwordx4 v[126:129], v[126:127], off offset:64
	s_waitcnt vmcnt(18)
	v_mfma_f32_16x16x32_bf16 v[48:51], v[90:93], v[244:247], v[48:51]
	v_mfma_f32_16x16x32_bf16 v[60:63], v[102:105], v[244:247], v[60:63]
	v_add_co_u32_e32 v244, vcc, s14, v180
	s_nop 1
	v_addc_co_u32_e32 v245, vcc, 0, v181, vcc
	global_load_dwordx4 v[130:133], v[244:245], off
	global_load_dwordx4 v[244:247], v[244:245], off offset:64
	s_waitcnt vmcnt(15)
	v_mfma_f32_16x16x32_bf16 v[56:59], v[162:165], v[86:89], v[56:59]
	v_mfma_f32_16x16x32_bf16 v[52:55], v[170:173], v[86:89], v[52:55]
	s_waitcnt vmcnt(14)
	v_mfma_f32_16x16x32_bf16 v[56:59], v[166:169], v[94:97], v[56:59]
	v_mfma_f32_16x16x32_bf16 v[52:55], v[174:177], v[94:97], v[52:55]
	s_waitcnt vmcnt(13)
	v_mfma_f32_16x16x32_bf16 v[40:43], v[162:165], v[216:219], v[40:43]
	v_mfma_f32_16x16x32_bf16 v[16:19], v[170:173], v[216:219], v[16:19]
	s_waitcnt vmcnt(12)
	v_mfma_f32_16x16x32_bf16 v[40:43], v[166:169], v[106:109], v[40:43]
	v_mfma_f32_16x16x32_bf16 v[16:19], v[174:177], v[106:109], v[16:19]
	s_waitcnt vmcnt(11)
	v_mfma_f32_16x16x32_bf16 v[12:15], v[162:165], v[220:223], v[12:15]
	v_mfma_f32_16x16x32_bf16 v[8:11], v[170:173], v[220:223], v[8:11]
	s_waitcnt vmcnt(10)
	v_mfma_f32_16x16x32_bf16 v[12:15], v[166:169], v[110:113], v[12:15]
	v_mfma_f32_16x16x32_bf16 v[8:11], v[174:177], v[110:113], v[8:11]
	s_waitcnt vmcnt(9)
	v_mfma_f32_16x16x32_bf16 v[4:7], v[162:165], v[224:227], v[4:7]
	v_mfma_f32_16x16x32_bf16 v[0:3], v[170:173], v[224:227], v[0:3]
	s_waitcnt vmcnt(8)
	v_mfma_f32_16x16x32_bf16 v[4:7], v[166:169], v[114:117], v[4:7]
	v_mfma_f32_16x16x32_bf16 v[0:3], v[174:177], v[114:117], v[0:3]
	s_waitcnt vmcnt(7)
	v_mfma_f32_16x16x32_bf16 v[20:23], v[162:165], v[232:235], v[20:23]
	v_mfma_f32_16x16x32_bf16 v[24:27], v[170:173], v[232:235], v[24:27]
	s_waitcnt vmcnt(6)
	v_mfma_f32_16x16x32_bf16 v[20:23], v[166:169], v[118:121], v[20:23]
	v_mfma_f32_16x16x32_bf16 v[24:27], v[174:177], v[118:121], v[24:27]
	s_waitcnt vmcnt(5)
	v_mfma_f32_16x16x32_bf16 v[28:31], v[162:165], v[236:239], v[28:31]
	v_mfma_f32_16x16x32_bf16 v[32:35], v[170:173], v[236:239], v[32:35]
	s_waitcnt vmcnt(4)
	v_mfma_f32_16x16x32_bf16 v[28:31], v[166:169], v[122:125], v[28:31]
	v_mfma_f32_16x16x32_bf16 v[32:35], v[174:177], v[122:125], v[32:35]
	s_waitcnt vmcnt(3)
	v_mfma_f32_16x16x32_bf16 v[36:39], v[162:165], v[240:243], v[36:39]
	v_mfma_f32_16x16x32_bf16 v[44:47], v[170:173], v[240:243], v[44:47]
	s_waitcnt vmcnt(1)
	v_mfma_f32_16x16x32_bf16 v[48:51], v[162:165], v[130:133], v[48:51]
	v_mfma_f32_16x16x32_bf16 v[60:63], v[170:173], v[130:133], v[60:63]
	v_mfma_f32_16x16x32_bf16 v[36:39], v[166:169], v[126:129], v[36:39]
	v_mfma_f32_16x16x32_bf16 v[44:47], v[174:177], v[126:129], v[44:47]
	s_waitcnt vmcnt(0)
	v_mfma_f32_16x16x32_bf16 v[48:51], v[166:169], v[244:247], v[48:51]
	v_mfma_f32_16x16x32_bf16 v[60:63], v[174:177], v[244:247], v[60:63]
	v_add_u32_e32 v66, s2, v75
	s_waitcnt lgkmcnt(0)
	s_barrier
	ds_write_b128 v66, v[56:59]
	ds_write_b128 v66, v[52:55] offset:1024
	ds_write_b128 v66, v[40:43] offset:2048
	ds_write_b128 v66, v[16:19] offset:3072
	ds_write_b128 v66, v[12:15] offset:4096
	ds_write_b128 v66, v[8:11] offset:5120
	ds_write_b128 v66, v[4:7] offset:6144
	ds_write_b128 v66, v[0:3] offset:7168
	ds_write_b128 v66, v[20:23] offset:8192
	ds_write_b128 v66, v[24:27] offset:9216
	ds_write_b128 v66, v[28:31] offset:10240
	ds_write_b128 v66, v[32:35] offset:11264
	ds_write_b128 v66, v[36:39] offset:12288
	ds_write_b128 v66, v[44:47] offset:13312
	ds_write_b128 v66, v[48:51] offset:14336
	ds_write_b128 v66, v[60:63] offset:15360
	s_waitcnt lgkmcnt(0)
	s_barrier
	v_add_u32_e32 v22, s3, v75
	ds_read_b128 v[0:3], v22
	ds_read_b128 v[4:7], v22 offset:16384
	ds_read_b128 v[8:11], v22 offset:32768
	ds_read_b128 v[12:15], v22 offset:1024
	ds_read_b128 v[16:19], v22 offset:17408
	s_mulk_i32 s16, 0xb0
	s_sub_i32 s0, s15, s16
	v_lshl_or_b32 v28, s0, 5, v76
	s_waitcnt lgkmcnt(3)
	v_pk_add_f32 v[6:7], v[2:3], v[6:7]
	v_pk_add_f32 v[20:21], v[0:1], v[4:5]
	ds_read_b128 v[0:3], v22 offset:33792
	s_waitcnt lgkmcnt(3)
	v_pk_add_f32 v[24:25], v[6:7], v[10:11]
	ds_read_b128 v[4:7], v22 offset:49152
	v_pk_add_f32 v[26:27], v[20:21], v[8:9]
	v_add_u32_e32 v8, s3, v77
	ds_read_b128 v[8:11], v8
	ds_read_b128 v[20:23], v22 offset:50176
	v_ashrrev_i32_e32 v29, 31, v28
	s_waitcnt lgkmcnt(2)
	v_pk_add_f32 v[26:27], v[26:27], v[4:5]
	v_add_u32_e32 v4, s3, v78
	v_pk_add_f32 v[24:25], v[24:25], v[6:7]
	ds_read_b128 v[4:7], v4
	s_waitcnt lgkmcnt(2)
	v_pk_add_f32 v[32:33], v[26:27], v[8:9]
	v_add_u32_e32 v8, s3, v79
	v_pk_add_f32 v[30:31], v[24:25], v[10:11]
	ds_read_b128 v[8:11], v8
	v_add_u32_e32 v24, s3, v80
	ds_read_b128 v[24:27], v24
	s_waitcnt lgkmcnt(2)
	v_pk_add_f32 v[6:7], v[30:31], v[6:7]
	v_pk_add_f32 v[4:5], v[32:33], v[4:5]
	s_waitcnt lgkmcnt(1)
	v_pk_add_f32 v[6:7], v[6:7], v[10:11]
	v_pk_add_f32 v[4:5], v[4:5], v[8:9]
	s_waitcnt lgkmcnt(0)
	v_pk_add_f32 v[6:7], v[6:7], v[26:27]
	v_pk_add_f32 v[4:5], v[4:5], v[24:25]
	v_lshl_add_u64 v[24:25], v[28:29], 1, v[64:65]
	v_cvt_pk_bf16_f32 v4, v4, v5
	v_cvt_pk_bf16_f32 v5, v6, v7
	v_pk_add_f32 v[6:7], v[12:13], v[16:17]
	global_store_dwordx2 v[24:25], v[4:5], off
	v_pk_add_f32 v[4:5], v[14:15], v[18:19]
	v_pk_add_f32 v[6:7], v[6:7], v[0:1]
	v_add_u32_e32 v0, s4, v77
	v_pk_add_f32 v[4:5], v[4:5], v[2:3]
	ds_read_b128 v[0:3], v0
	v_pk_add_f32 v[8:9], v[4:5], v[22:23]
	v_pk_add_f32 v[10:11], v[6:7], v[20:21]
	v_add_u32_e32 v4, s4, v78
	ds_read_b128 v[4:7], v4
	s_waitcnt lgkmcnt(1)
	v_pk_add_f32 v[14:15], v[10:11], v[0:1]
	v_add_u32_e32 v0, s4, v79
	v_pk_add_f32 v[12:13], v[8:9], v[2:3]
	ds_read_b128 v[0:3], v0
	v_add_u32_e32 v8, s4, v80
	ds_read_b128 v[8:11], v8
	s_waitcnt lgkmcnt(2)
	v_pk_add_f32 v[6:7], v[12:13], v[6:7]
	v_pk_add_f32 v[4:5], v[14:15], v[4:5]
	s_waitcnt lgkmcnt(1)
	v_pk_add_f32 v[2:3], v[6:7], v[2:3]
	v_pk_add_f32 v[0:1], v[4:5], v[0:1]
	s_waitcnt lgkmcnt(0)
	v_pk_add_f32 v[2:3], v[2:3], v[10:11]
	v_pk_add_f32 v[0:1], v[0:1], v[8:9]
	s_add_i32 s15, s15, s52
	v_cvt_pk_bf16_f32 v0, v0, v1
	v_cvt_pk_bf16_f32 v1, v2, v3
	s_cmpk_gt_i32 s15, 0xaf
	global_store_dwordx2 v[24:25], v[0:1], off offset:32
	s_cbranch_scc0 .LBB0_140

.LBB0_350:
	v_lshl_add_u64 v[82:83], v[70:71], 0, s[0:1]
	v_add_co_u32_e32 v98, vcc, s7, v82
	v_lshl_add_u64 v[126:127], v[72:73], 0, s[0:1]
	s_nop 1
	v_addc_co_u32_e32 v99, vcc, 0, v83, vcc
	v_add_co_u32_e32 v106, vcc, s8, v82
	s_add_u32 s0, s0, 0x80
	s_nop 1
	v_addc_co_u32_e32 v107, vcc, 0, v83, vcc
	v_add_co_u32_e32 v100, vcc, s9, v126
	s_addc_u32 s1, s1, 0
	s_nop 1
	v_addc_co_u32_e32 v101, vcc, 0, v127, vcc
	v_add_co_u32_e32 v110, vcc, s10, v126
	s_cmpk_eq_i32 s0, 0x100
	s_nop 1
	v_addc_co_u32_e32 v111, vcc, 0, v127, vcc
	v_add_co_u32_e32 v114, vcc, s11, v126
	s_nop 1
	v_addc_co_u32_e32 v115, vcc, 0, v127, vcc
	v_add_co_u32_e32 v118, vcc, s12, v126
	s_nop 1
	v_addc_co_u32_e32 v119, vcc, 0, v127, vcc
	v_add_co_u32_e32 v120, vcc, s13, v126
	s_nop 1
	v_addc_co_u32_e32 v121, vcc, 0, v127, vcc
	v_add_co_u32_e32 v122, vcc, s14, v126
	s_nop 1
	v_addc_co_u32_e32 v123, vcc, 0, v127, vcc
	v_add_co_u32_e32 v128, vcc, s15, v126
	s_nop 1
	v_addc_co_u32_e32 v129, vcc, 0, v127, vcc
	v_add_co_u32_e32 v134, vcc, s16, v126
	s_nop 1
	v_addc_co_u32_e32 v135, vcc, 0, v127, vcc
	global_load_dwordx4 v[82:85], v[98:99], off
	global_load_dwordx4 v[86:89], v[100:101], off
	global_load_dwordx4 v[90:93], v[98:99], off offset:64
	global_load_dwordx4 v[94:97], v[100:101], off offset:64
	global_load_dwordx4 v[98:101], v[106:107], off
	global_load_dwordx4 v[102:105], v[106:107], off offset:64
	global_load_dwordx4 v[216:219], v[110:111], off
	global_load_dwordx4 v[106:109], v[110:111], off offset:64
	global_load_dwordx4 v[220:223], v[114:115], off
	global_load_dwordx4 v[110:113], v[114:115], off offset:64
	global_load_dwordx4 v[224:227], v[118:119], off
	global_load_dwordx4 v[114:117], v[118:119], off offset:64
	global_load_dwordx4 v[234:237], v[120:121], off
	global_load_dwordx4 v[118:121], v[120:121], off offset:64
	global_load_dwordx4 v[238:241], v[122:123], off
	global_load_dwordx4 v[122:125], v[122:123], off offset:64
	global_load_dwordx4 v[242:245], v[128:129], off
	global_load_dwordx4 v[126:129], v[128:129], off offset:64
	global_load_dwordx4 v[130:133], v[134:135], off
	global_load_dwordx4 v[246:249], v[134:135], off offset:64
	v_lshl_add_u64 v[178:179], v[70:71], 0, s[0:1]
	v_lshl_add_u64 v[180:181], v[72:73], 0, s[0:1]
	s_add_u32 s0, s0, 0x80
	s_addc_u32 s1, s1, 0
	s_cmpk_eq_i32 s0, 0x100
	v_add_co_u32_e32 v166, vcc, s7, v178
	s_nop 1
	v_addc_co_u32_e32 v167, vcc, 0, v179, vcc
	global_load_dwordx4 v[162:165], v[166:167], off
	global_load_dwordx4 v[166:169], v[166:167], off offset:64
	v_add_co_u32_e32 v174, vcc, s8, v178
	s_nop 1
	v_addc_co_u32_e32 v175, vcc, 0, v179, vcc
	global_load_dwordx4 v[170:173], v[174:175], off
	global_load_dwordx4 v[174:177], v[174:175], off offset:64
	s_waitcnt vmcnt(22)
	v_mfma_f32_16x16x32_bf16 v[56:59], v[82:85], v[86:89], v[56:59]
	s_waitcnt vmcnt(19)
	v_mfma_f32_16x16x32_bf16 v[52:55], v[98:101], v[86:89], v[52:55]
	v_mfma_f32_16x16x32_bf16 v[56:59], v[90:93], v[94:97], v[56:59]
	s_waitcnt vmcnt(18)
	v_mfma_f32_16x16x32_bf16 v[52:55], v[102:105], v[94:97], v[52:55]
	v_add_co_u32_e32 v94, vcc, s9, v180
	s_nop 1
	v_addc_co_u32_e32 v95, vcc, 0, v181, vcc
	global_load_dwordx4 v[86:89], v[94:95], off
	global_load_dwordx4 v[94:97], v[94:95], off offset:64
	s_waitcnt vmcnt(19)
	v_mfma_f32_16x16x32_bf16 v[44:47], v[82:85], v[216:219], v[44:47]
	v_mfma_f32_16x16x32_bf16 v[20:23], v[98:101], v[216:219], v[20:23]
	s_waitcnt vmcnt(18)
	v_mfma_f32_16x16x32_bf16 v[44:47], v[90:93], v[106:109], v[44:47]
	v_mfma_f32_16x16x32_bf16 v[20:23], v[102:105], v[106:109], v[20:23]
	v_add_co_u32_e32 v106, vcc, s10, v180
	s_nop 1
	v_addc_co_u32_e32 v107, vcc, 0, v181, vcc
	global_load_dwordx4 v[216:219], v[106:107], off
	global_load_dwordx4 v[106:109], v[106:107], off offset:64
	s_waitcnt vmcnt(19)
	v_mfma_f32_16x16x32_bf16 v[12:15], v[82:85], v[220:223], v[12:15]
	v_mfma_f32_16x16x32_bf16 v[8:11], v[98:101], v[220:223], v[8:11]
	s_waitcnt vmcnt(18)
	v_mfma_f32_16x16x32_bf16 v[12:15], v[90:93], v[110:113], v[12:15]
	v_mfma_f32_16x16x32_bf16 v[8:11], v[102:105], v[110:113], v[8:11]
	v_add_co_u32_e32 v110, vcc, s11, v180
	s_nop 1
	v_addc_co_u32_e32 v111, vcc, 0, v181, vcc
	global_load_dwordx4 v[220:223], v[110:111], off
	global_load_dwordx4 v[110:113], v[110:111], off offset:64
	s_waitcnt vmcnt(19)
	v_mfma_f32_16x16x32_bf16 v[4:7], v[82:85], v[224:227], v[4:7]
	v_mfma_f32_16x16x32_bf16 v[0:3], v[98:101], v[224:227], v[0:3]
	s_waitcnt vmcnt(18)
	v_mfma_f32_16x16x32_bf16 v[4:7], v[90:93], v[114:117], v[4:7]
	v_mfma_f32_16x16x32_bf16 v[0:3], v[102:105], v[114:117], v[0:3]
	v_add_co_u32_e32 v114, vcc, s12, v180
	s_nop 1
	v_addc_co_u32_e32 v115, vcc, 0, v181, vcc
	global_load_dwordx4 v[224:227], v[114:115], off
	global_load_dwordx4 v[114:117], v[114:115], off offset:64
	s_waitcnt vmcnt(19)
	v_mfma_f32_16x16x32_bf16 v[16:19], v[82:85], v[234:237], v[16:19]
	v_mfma_f32_16x16x32_bf16 v[24:27], v[98:101], v[234:237], v[24:27]
	s_waitcnt vmcnt(18)
	v_mfma_f32_16x16x32_bf16 v[16:19], v[90:93], v[118:121], v[16:19]
	v_mfma_f32_16x16x32_bf16 v[24:27], v[102:105], v[118:121], v[24:27]
	v_add_co_u32_e32 v118, vcc, s13, v180
	s_nop 1
	v_addc_co_u32_e32 v119, vcc, 0, v181, vcc
	global_load_dwordx4 v[234:237], v[118:119], off
	global_load_dwordx4 v[118:121], v[118:119], off offset:64
	s_waitcnt vmcnt(19)
	v_mfma_f32_16x16x32_bf16 v[28:31], v[82:85], v[238:241], v[28:31]
	v_mfma_f32_16x16x32_bf16 v[32:35], v[98:101], v[238:241], v[32:35]
	s_waitcnt vmcnt(18)
	v_mfma_f32_16x16x32_bf16 v[28:31], v[90:93], v[122:125], v[28:31]
	v_mfma_f32_16x16x32_bf16 v[32:35], v[102:105], v[122:125], v[32:35]
	v_add_co_u32_e32 v122, vcc, s14, v180
	s_nop 1
	v_addc_co_u32_e32 v123, vcc, 0, v181, vcc
	global_load_dwordx4 v[238:241], v[122:123], off
	global_load_dwordx4 v[122:125], v[122:123], off offset:64
	s_waitcnt vmcnt(19)
	v_mfma_f32_16x16x32_bf16 v[36:39], v[82:85], v[242:245], v[36:39]
	v_mfma_f32_16x16x32_bf16 v[40:43], v[98:101], v[242:245], v[40:43]
	s_waitcnt vmcnt(17)
	v_mfma_f32_16x16x32_bf16 v[48:51], v[82:85], v[130:133], v[48:51]
	v_mfma_f32_16x16x32_bf16 v[60:63], v[98:101], v[130:133], v[60:63]
	v_mfma_f32_16x16x32_bf16 v[36:39], v[90:93], v[126:129], v[36:39]
	v_mfma_f32_16x16x32_bf16 v[40:43], v[102:105], v[126:129], v[40:43]
	v_add_co_u32_e32 v126, vcc, s15, v180
	s_nop 1
	v_addc_co_u32_e32 v127, vcc, 0, v181, vcc
	global_load_dwordx4 v[242:245], v[126:127], off
	global_load_dwordx4 v[126:129], v[126:127], off offset:64
	s_waitcnt vmcnt(18)
	v_mfma_f32_16x16x32_bf16 v[48:51], v[90:93], v[246:249], v[48:51]
	v_mfma_f32_16x16x32_bf16 v[60:63], v[102:105], v[246:249], v[60:63]
	v_add_co_u32_e32 v246, vcc, s16, v180
	s_nop 1
	v_addc_co_u32_e32 v247, vcc, 0, v181, vcc
	global_load_dwordx4 v[130:133], v[246:247], off
	global_load_dwordx4 v[246:249], v[246:247], off offset:64
	s_waitcnt vmcnt(15)
	v_mfma_f32_16x16x32_bf16 v[56:59], v[162:165], v[86:89], v[56:59]
	v_mfma_f32_16x16x32_bf16 v[52:55], v[170:173], v[86:89], v[52:55]
	s_waitcnt vmcnt(14)
	v_mfma_f32_16x16x32_bf16 v[56:59], v[166:169], v[94:97], v[56:59]
	v_mfma_f32_16x16x32_bf16 v[52:55], v[174:177], v[94:97], v[52:55]
	s_waitcnt vmcnt(13)
	v_mfma_f32_16x16x32_bf16 v[44:47], v[162:165], v[216:219], v[44:47]
	v_mfma_f32_16x16x32_bf16 v[20:23], v[170:173], v[216:219], v[20:23]
	s_waitcnt vmcnt(12)
	v_mfma_f32_16x16x32_bf16 v[44:47], v[166:169], v[106:109], v[44:47]
	v_mfma_f32_16x16x32_bf16 v[20:23], v[174:177], v[106:109], v[20:23]
	s_waitcnt vmcnt(11)
	v_mfma_f32_16x16x32_bf16 v[12:15], v[162:165], v[220:223], v[12:15]
	v_mfma_f32_16x16x32_bf16 v[8:11], v[170:173], v[220:223], v[8:11]
	s_waitcnt vmcnt(10)
	v_mfma_f32_16x16x32_bf16 v[12:15], v[166:169], v[110:113], v[12:15]
	v_mfma_f32_16x16x32_bf16 v[8:11], v[174:177], v[110:113], v[8:11]
	s_waitcnt vmcnt(9)
	v_mfma_f32_16x16x32_bf16 v[4:7], v[162:165], v[224:227], v[4:7]
	v_mfma_f32_16x16x32_bf16 v[0:3], v[170:173], v[224:227], v[0:3]
	s_waitcnt vmcnt(8)
	v_mfma_f32_16x16x32_bf16 v[4:7], v[166:169], v[114:117], v[4:7]
	v_mfma_f32_16x16x32_bf16 v[0:3], v[174:177], v[114:117], v[0:3]
	s_waitcnt vmcnt(7)
	v_mfma_f32_16x16x32_bf16 v[16:19], v[162:165], v[234:237], v[16:19]
	v_mfma_f32_16x16x32_bf16 v[24:27], v[170:173], v[234:237], v[24:27]
	s_waitcnt vmcnt(6)
	v_mfma_f32_16x16x32_bf16 v[16:19], v[166:169], v[118:121], v[16:19]
	v_mfma_f32_16x16x32_bf16 v[24:27], v[174:177], v[118:121], v[24:27]
	s_waitcnt vmcnt(5)
	v_mfma_f32_16x16x32_bf16 v[28:31], v[162:165], v[238:241], v[28:31]
	v_mfma_f32_16x16x32_bf16 v[32:35], v[170:173], v[238:241], v[32:35]
	s_waitcnt vmcnt(4)
	v_mfma_f32_16x16x32_bf16 v[28:31], v[166:169], v[122:125], v[28:31]
	v_mfma_f32_16x16x32_bf16 v[32:35], v[174:177], v[122:125], v[32:35]
	s_waitcnt vmcnt(3)
	v_mfma_f32_16x16x32_bf16 v[36:39], v[162:165], v[242:245], v[36:39]
	v_mfma_f32_16x16x32_bf16 v[40:43], v[170:173], v[242:245], v[40:43]
	s_waitcnt vmcnt(1)
	v_mfma_f32_16x16x32_bf16 v[48:51], v[162:165], v[130:133], v[48:51]
	v_mfma_f32_16x16x32_bf16 v[60:63], v[170:173], v[130:133], v[60:63]
	v_mfma_f32_16x16x32_bf16 v[36:39], v[166:169], v[126:129], v[36:39]
	v_mfma_f32_16x16x32_bf16 v[40:43], v[174:177], v[126:129], v[40:43]
	s_waitcnt vmcnt(0)
	v_mfma_f32_16x16x32_bf16 v[48:51], v[166:169], v[246:249], v[48:51]
	v_mfma_f32_16x16x32_bf16 v[60:63], v[174:177], v[246:249], v[60:63]
	v_add_u32_e32 v66, s4, v75
	s_waitcnt lgkmcnt(0)
	s_barrier
	ds_write_b128 v66, v[56:59]
	ds_write_b128 v66, v[52:55] offset:1024
	ds_write_b128 v66, v[44:47] offset:2048
	ds_write_b128 v66, v[20:23] offset:3072
	ds_write_b128 v66, v[12:15] offset:4096
	ds_write_b128 v66, v[8:11] offset:5120
	ds_write_b128 v66, v[4:7] offset:6144
	ds_write_b128 v66, v[0:3] offset:7168
	ds_write_b128 v66, v[16:19] offset:8192
	ds_write_b128 v66, v[24:27] offset:9216
	ds_write_b128 v66, v[28:31] offset:10240
	ds_write_b128 v66, v[32:35] offset:11264
	ds_write_b128 v66, v[36:39] offset:12288
	ds_write_b128 v66, v[40:43] offset:13312
	ds_write_b128 v66, v[48:51] offset:14336
	ds_write_b128 v66, v[60:63] offset:15360
	s_waitcnt lgkmcnt(0)
	s_barrier
	v_add_u32_e32 v22, s5, v75
	ds_read_b128 v[0:3], v22
	ds_read_b128 v[4:7], v22 offset:16384
	ds_read_b128 v[8:11], v22 offset:32768
	ds_read_b128 v[12:15], v22 offset:1024
	ds_read_b128 v[16:19], v22 offset:17408
	s_lshl_b32 s0, s17, 5
	s_sub_i32 s0, s3, s0
	v_lshl_or_b32 v28, s0, 5, v76
	s_waitcnt lgkmcnt(3)
	v_pk_add_f32 v[6:7], v[2:3], v[6:7]
	v_pk_add_f32 v[20:21], v[0:1], v[4:5]
	ds_read_b128 v[0:3], v22 offset:33792
	s_waitcnt lgkmcnt(3)
	v_pk_add_f32 v[24:25], v[6:7], v[10:11]
	ds_read_b128 v[4:7], v22 offset:49152
	v_pk_add_f32 v[26:27], v[20:21], v[8:9]
	v_add_u32_e32 v8, s5, v77
	ds_read_b128 v[8:11], v8
	ds_read_b128 v[20:23], v22 offset:50176
	v_ashrrev_i32_e32 v29, 31, v28
	s_waitcnt lgkmcnt(2)
	v_pk_add_f32 v[26:27], v[26:27], v[4:5]
	v_add_u32_e32 v4, s5, v78
	v_pk_add_f32 v[24:25], v[24:25], v[6:7]
	ds_read_b128 v[4:7], v4
	s_waitcnt lgkmcnt(2)
	v_pk_add_f32 v[32:33], v[26:27], v[8:9]
	v_add_u32_e32 v8, s5, v79
	v_pk_add_f32 v[30:31], v[24:25], v[10:11]
	ds_read_b128 v[8:11], v8
	v_add_u32_e32 v24, s5, v80
	ds_read_b128 v[24:27], v24
	s_waitcnt lgkmcnt(2)
	v_pk_add_f32 v[6:7], v[30:31], v[6:7]
	v_pk_add_f32 v[4:5], v[32:33], v[4:5]
	s_waitcnt lgkmcnt(1)
	v_pk_add_f32 v[6:7], v[6:7], v[10:11]
	v_pk_add_f32 v[4:5], v[4:5], v[8:9]
	s_waitcnt lgkmcnt(0)
	v_pk_add_f32 v[6:7], v[6:7], v[26:27]
	v_pk_add_f32 v[4:5], v[4:5], v[24:25]
	v_lshl_add_u64 v[24:25], v[28:29], 2, v[64:65]
	global_store_dwordx4 v[24:25], v[4:7], off
	s_add_i32 s3, s3, s2
	s_cmp_gt_i32 s3, 31
	v_pk_add_f32 v[6:7], v[12:13], v[16:17]
	v_pk_add_f32 v[4:5], v[14:15], v[18:19]
	v_pk_add_f32 v[6:7], v[6:7], v[0:1]
	v_add_u32_e32 v0, s6, v77
	v_pk_add_f32 v[4:5], v[4:5], v[2:3]
	ds_read_b128 v[0:3], v0
	v_pk_add_f32 v[8:9], v[4:5], v[22:23]
	v_pk_add_f32 v[10:11], v[6:7], v[20:21]
	v_add_u32_e32 v4, s6, v78
	ds_read_b128 v[4:7], v4
	s_waitcnt lgkmcnt(1)
	v_pk_add_f32 v[14:15], v[10:11], v[0:1]
	v_add_u32_e32 v0, s6, v79
	v_pk_add_f32 v[12:13], v[8:9], v[2:3]
	ds_read_b128 v[0:3], v0
	v_add_u32_e32 v8, s6, v80
	ds_read_b128 v[8:11], v8
	s_waitcnt lgkmcnt(2)
	v_pk_add_f32 v[6:7], v[12:13], v[6:7]
	v_pk_add_f32 v[4:5], v[14:15], v[4:5]
	s_waitcnt lgkmcnt(1)
	v_pk_add_f32 v[2:3], v[6:7], v[2:3]
	v_pk_add_f32 v[0:1], v[4:5], v[0:1]
	s_waitcnt lgkmcnt(0)
	v_pk_add_f32 v[2:3], v[2:3], v[10:11]
	v_pk_add_f32 v[0:1], v[0:1], v[8:9]
	global_store_dwordx4 v[24:25], v[0:3], off offset:64
	s_cbranch_scc0 .LBB0_349

.LBB0_522:
	v_lshl_add_u64 v[84:85], v[72:73], 0, s[0:1]
	v_add_co_u32_e32 v100, vcc, s5, v84
	v_lshl_add_u64 v[128:129], v[74:75], 0, s[0:1]
	s_nop 1
	v_addc_co_u32_e32 v101, vcc, 0, v85, vcc
	v_add_co_u32_e32 v108, vcc, s6, v84
	s_add_u32 s0, s0, 0x80
	s_nop 1
	v_addc_co_u32_e32 v109, vcc, 0, v85, vcc
	v_add_co_u32_e32 v102, vcc, s7, v128
	s_addc_u32 s1, s1, 0
	s_nop 1
	v_addc_co_u32_e32 v103, vcc, 0, v129, vcc
	v_add_co_u32_e32 v112, vcc, s8, v128
	s_cmpk_eq_i32 s0, 0x100
	s_nop 1
	v_addc_co_u32_e32 v113, vcc, 0, v129, vcc
	v_add_co_u32_e32 v116, vcc, s9, v128
	s_nop 1
	v_addc_co_u32_e32 v117, vcc, 0, v129, vcc
	v_add_co_u32_e32 v120, vcc, s10, v128
	s_nop 1
	v_addc_co_u32_e32 v121, vcc, 0, v129, vcc
	v_add_co_u32_e32 v122, vcc, s11, v128
	s_nop 1
	v_addc_co_u32_e32 v123, vcc, 0, v129, vcc
	v_add_co_u32_e32 v124, vcc, s20, v128
	s_nop 1
	v_addc_co_u32_e32 v125, vcc, 0, v129, vcc
	v_add_co_u32_e32 v130, vcc, s21, v128
	s_nop 1
	v_addc_co_u32_e32 v131, vcc, 0, v129, vcc
	v_add_co_u32_e32 v136, vcc, s22, v128
	s_nop 1
	v_addc_co_u32_e32 v137, vcc, 0, v129, vcc
	global_load_dwordx4 v[84:87], v[100:101], off
	global_load_dwordx4 v[88:91], v[102:103], off
	global_load_dwordx4 v[92:95], v[100:101], off offset:64
	global_load_dwordx4 v[96:99], v[102:103], off offset:64
	global_load_dwordx4 v[100:103], v[108:109], off
	global_load_dwordx4 v[104:107], v[108:109], off offset:64
	global_load_dwordx4 v[218:221], v[112:113], off
	global_load_dwordx4 v[108:111], v[112:113], off offset:64
	global_load_dwordx4 v[222:225], v[116:117], off
	global_load_dwordx4 v[112:115], v[116:117], off offset:64
	global_load_dwordx4 v[230:233], v[120:121], off
	global_load_dwordx4 v[116:119], v[120:121], off offset:64
	global_load_dwordx4 v[234:237], v[122:123], off
	global_load_dwordx4 v[120:123], v[122:123], off offset:64
	global_load_dwordx4 v[238:241], v[124:125], off
	global_load_dwordx4 v[124:127], v[124:125], off offset:64
	global_load_dwordx4 v[242:245], v[130:131], off
	global_load_dwordx4 v[128:131], v[130:131], off offset:64
	global_load_dwordx4 v[132:135], v[136:137], off
	global_load_dwordx4 v[246:249], v[136:137], off offset:64
	v_lshl_add_u64 v[212:213], v[72:73], 0, s[0:1]
	v_lshl_add_u64 v[214:215], v[74:75], 0, s[0:1]
	s_add_u32 s0, s0, 0x80
	s_addc_u32 s1, s1, 0
	s_cmpk_eq_i32 s0, 0x100
	v_add_co_u32_e32 v192, vcc, s5, v212
	s_nop 1
	v_addc_co_u32_e32 v193, vcc, 0, v213, vcc
	global_load_dwordx4 v[188:191], v[192:193], off
	global_load_dwordx4 v[192:195], v[192:193], off offset:64
	v_add_co_u32_e32 v208, vcc, s6, v212
	s_nop 1
	v_addc_co_u32_e32 v209, vcc, 0, v213, vcc
	global_load_dwordx4 v[200:203], v[208:209], off
	global_load_dwordx4 v[208:211], v[208:209], off offset:64
	s_waitcnt vmcnt(22)
	v_mfma_f32_16x16x32_bf16 v[56:59], v[84:87], v[88:91], v[56:59]
	s_waitcnt vmcnt(19)
	v_mfma_f32_16x16x32_bf16 v[52:55], v[100:103], v[88:91], v[52:55]
	v_mfma_f32_16x16x32_bf16 v[56:59], v[92:95], v[96:99], v[56:59]
	s_waitcnt vmcnt(18)
	v_mfma_f32_16x16x32_bf16 v[52:55], v[104:107], v[96:99], v[52:55]
	v_add_co_u32_e32 v96, vcc, s7, v214
	s_nop 1
	v_addc_co_u32_e32 v97, vcc, 0, v215, vcc
	global_load_dwordx4 v[88:91], v[96:97], off
	global_load_dwordx4 v[96:99], v[96:97], off offset:64
	s_waitcnt vmcnt(19)
	v_mfma_f32_16x16x32_bf16 v[44:47], v[84:87], v[218:221], v[44:47]
	v_mfma_f32_16x16x32_bf16 v[20:23], v[100:103], v[218:221], v[20:23]
	s_waitcnt vmcnt(18)
	v_mfma_f32_16x16x32_bf16 v[44:47], v[92:95], v[108:111], v[44:47]
	v_mfma_f32_16x16x32_bf16 v[20:23], v[104:107], v[108:111], v[20:23]
	v_add_co_u32_e32 v108, vcc, s8, v214
	s_nop 1
	v_addc_co_u32_e32 v109, vcc, 0, v215, vcc
	global_load_dwordx4 v[218:221], v[108:109], off
	global_load_dwordx4 v[108:111], v[108:109], off offset:64
	s_waitcnt vmcnt(19)
	v_mfma_f32_16x16x32_bf16 v[12:15], v[84:87], v[222:225], v[12:15]
	v_mfma_f32_16x16x32_bf16 v[8:11], v[100:103], v[222:225], v[8:11]
	s_waitcnt vmcnt(18)
	v_mfma_f32_16x16x32_bf16 v[12:15], v[92:95], v[112:115], v[12:15]
	v_mfma_f32_16x16x32_bf16 v[8:11], v[104:107], v[112:115], v[8:11]
	v_add_co_u32_e32 v112, vcc, s9, v214
	s_nop 1
	v_addc_co_u32_e32 v113, vcc, 0, v215, vcc
	global_load_dwordx4 v[222:225], v[112:113], off
	global_load_dwordx4 v[112:115], v[112:113], off offset:64
	s_waitcnt vmcnt(19)
	v_mfma_f32_16x16x32_bf16 v[4:7], v[84:87], v[230:233], v[4:7]
	v_mfma_f32_16x16x32_bf16 v[0:3], v[100:103], v[230:233], v[0:3]
	s_waitcnt vmcnt(18)
	v_mfma_f32_16x16x32_bf16 v[4:7], v[92:95], v[116:119], v[4:7]
	v_mfma_f32_16x16x32_bf16 v[0:3], v[104:107], v[116:119], v[0:3]
	v_add_co_u32_e32 v116, vcc, s10, v214
	s_nop 1
	v_addc_co_u32_e32 v117, vcc, 0, v215, vcc
	global_load_dwordx4 v[230:233], v[116:117], off
	global_load_dwordx4 v[116:119], v[116:117], off offset:64
	s_waitcnt vmcnt(19)
	v_mfma_f32_16x16x32_bf16 v[16:19], v[84:87], v[234:237], v[16:19]
	v_mfma_f32_16x16x32_bf16 v[24:27], v[100:103], v[234:237], v[24:27]
	s_waitcnt vmcnt(18)
	v_mfma_f32_16x16x32_bf16 v[16:19], v[92:95], v[120:123], v[16:19]
	v_mfma_f32_16x16x32_bf16 v[24:27], v[104:107], v[120:123], v[24:27]
	v_add_co_u32_e32 v120, vcc, s11, v214
	s_nop 1
	v_addc_co_u32_e32 v121, vcc, 0, v215, vcc
	global_load_dwordx4 v[234:237], v[120:121], off
	global_load_dwordx4 v[120:123], v[120:121], off offset:64
	s_waitcnt vmcnt(19)
	v_mfma_f32_16x16x32_bf16 v[28:31], v[84:87], v[238:241], v[28:31]
	v_mfma_f32_16x16x32_bf16 v[32:35], v[100:103], v[238:241], v[32:35]
	s_waitcnt vmcnt(18)
	v_mfma_f32_16x16x32_bf16 v[28:31], v[92:95], v[124:127], v[28:31]
	v_mfma_f32_16x16x32_bf16 v[32:35], v[104:107], v[124:127], v[32:35]
	v_add_co_u32_e32 v124, vcc, s20, v214
	s_nop 1
	v_addc_co_u32_e32 v125, vcc, 0, v215, vcc
	global_load_dwordx4 v[238:241], v[124:125], off
	global_load_dwordx4 v[124:127], v[124:125], off offset:64
	s_waitcnt vmcnt(19)
	v_mfma_f32_16x16x32_bf16 v[36:39], v[84:87], v[242:245], v[36:39]
	v_mfma_f32_16x16x32_bf16 v[40:43], v[100:103], v[242:245], v[40:43]
	s_waitcnt vmcnt(17)
	v_mfma_f32_16x16x32_bf16 v[48:51], v[84:87], v[132:135], v[48:51]
	v_mfma_f32_16x16x32_bf16 v[60:63], v[100:103], v[132:135], v[60:63]
	v_mfma_f32_16x16x32_bf16 v[36:39], v[92:95], v[128:131], v[36:39]
	v_mfma_f32_16x16x32_bf16 v[40:43], v[104:107], v[128:131], v[40:43]
	v_add_co_u32_e32 v128, vcc, s21, v214
	s_nop 1
	v_addc_co_u32_e32 v129, vcc, 0, v215, vcc
	global_load_dwordx4 v[242:245], v[128:129], off
	global_load_dwordx4 v[128:131], v[128:129], off offset:64
	s_waitcnt vmcnt(18)
	v_mfma_f32_16x16x32_bf16 v[48:51], v[92:95], v[246:249], v[48:51]
	v_mfma_f32_16x16x32_bf16 v[60:63], v[104:107], v[246:249], v[60:63]
	v_add_co_u32_e32 v246, vcc, s22, v214
	s_nop 1
	v_addc_co_u32_e32 v247, vcc, 0, v215, vcc
	global_load_dwordx4 v[132:135], v[246:247], off
	global_load_dwordx4 v[246:249], v[246:247], off offset:64
	s_waitcnt vmcnt(15)
	v_mfma_f32_16x16x32_bf16 v[56:59], v[188:191], v[88:91], v[56:59]
	v_mfma_f32_16x16x32_bf16 v[52:55], v[200:203], v[88:91], v[52:55]
	s_waitcnt vmcnt(14)
	v_mfma_f32_16x16x32_bf16 v[56:59], v[192:195], v[96:99], v[56:59]
	v_mfma_f32_16x16x32_bf16 v[52:55], v[208:211], v[96:99], v[52:55]
	s_waitcnt vmcnt(13)
	v_mfma_f32_16x16x32_bf16 v[44:47], v[188:191], v[218:221], v[44:47]
	v_mfma_f32_16x16x32_bf16 v[20:23], v[200:203], v[218:221], v[20:23]
	s_waitcnt vmcnt(12)
	v_mfma_f32_16x16x32_bf16 v[44:47], v[192:195], v[108:111], v[44:47]
	v_mfma_f32_16x16x32_bf16 v[20:23], v[208:211], v[108:111], v[20:23]
	s_waitcnt vmcnt(11)
	v_mfma_f32_16x16x32_bf16 v[12:15], v[188:191], v[222:225], v[12:15]
	v_mfma_f32_16x16x32_bf16 v[8:11], v[200:203], v[222:225], v[8:11]
	s_waitcnt vmcnt(10)
	v_mfma_f32_16x16x32_bf16 v[12:15], v[192:195], v[112:115], v[12:15]
	v_mfma_f32_16x16x32_bf16 v[8:11], v[208:211], v[112:115], v[8:11]
	s_waitcnt vmcnt(9)
	v_mfma_f32_16x16x32_bf16 v[4:7], v[188:191], v[230:233], v[4:7]
	v_mfma_f32_16x16x32_bf16 v[0:3], v[200:203], v[230:233], v[0:3]
	s_waitcnt vmcnt(8)
	v_mfma_f32_16x16x32_bf16 v[4:7], v[192:195], v[116:119], v[4:7]
	v_mfma_f32_16x16x32_bf16 v[0:3], v[208:211], v[116:119], v[0:3]
	s_waitcnt vmcnt(7)
	v_mfma_f32_16x16x32_bf16 v[16:19], v[188:191], v[234:237], v[16:19]
	v_mfma_f32_16x16x32_bf16 v[24:27], v[200:203], v[234:237], v[24:27]
	s_waitcnt vmcnt(6)
	v_mfma_f32_16x16x32_bf16 v[16:19], v[192:195], v[120:123], v[16:19]
	v_mfma_f32_16x16x32_bf16 v[24:27], v[208:211], v[120:123], v[24:27]
	s_waitcnt vmcnt(5)
	v_mfma_f32_16x16x32_bf16 v[28:31], v[188:191], v[238:241], v[28:31]
	v_mfma_f32_16x16x32_bf16 v[32:35], v[200:203], v[238:241], v[32:35]
	s_waitcnt vmcnt(4)
	v_mfma_f32_16x16x32_bf16 v[28:31], v[192:195], v[124:127], v[28:31]
	v_mfma_f32_16x16x32_bf16 v[32:35], v[208:211], v[124:127], v[32:35]
	s_waitcnt vmcnt(3)
	v_mfma_f32_16x16x32_bf16 v[36:39], v[188:191], v[242:245], v[36:39]
	v_mfma_f32_16x16x32_bf16 v[40:43], v[200:203], v[242:245], v[40:43]
	s_waitcnt vmcnt(1)
	v_mfma_f32_16x16x32_bf16 v[48:51], v[188:191], v[132:135], v[48:51]
	v_mfma_f32_16x16x32_bf16 v[60:63], v[200:203], v[132:135], v[60:63]
	v_mfma_f32_16x16x32_bf16 v[36:39], v[192:195], v[128:131], v[36:39]
	v_mfma_f32_16x16x32_bf16 v[40:43], v[208:211], v[128:131], v[40:43]
	s_waitcnt vmcnt(0)
	v_mfma_f32_16x16x32_bf16 v[48:51], v[192:195], v[246:249], v[48:51]
	v_mfma_f32_16x16x32_bf16 v[60:63], v[208:211], v[246:249], v[60:63]
	v_add_u32_e32 v68, s2, v77
	s_waitcnt lgkmcnt(0)
	s_barrier
	ds_write_b128 v68, v[56:59]
	ds_write_b128 v68, v[52:55] offset:1024
	ds_write_b128 v68, v[44:47] offset:2048
	ds_write_b128 v68, v[20:23] offset:3072
	ds_write_b128 v68, v[12:15] offset:4096
	ds_write_b128 v68, v[8:11] offset:5120
	ds_write_b128 v68, v[4:7] offset:6144
	ds_write_b128 v68, v[0:3] offset:7168
	ds_write_b128 v68, v[16:19] offset:8192
	ds_write_b128 v68, v[24:27] offset:9216
	ds_write_b128 v68, v[28:31] offset:10240
	ds_write_b128 v68, v[32:35] offset:11264
	ds_write_b128 v68, v[36:39] offset:12288
	ds_write_b128 v68, v[40:43] offset:13312
	ds_write_b128 v68, v[48:51] offset:14336
	ds_write_b128 v68, v[60:63] offset:15360
	s_waitcnt lgkmcnt(0)
	s_barrier
	global_load_dword v50, v[64:65], off
	v_add_u32_e32 v44, s3, v77
	v_add_u32_e32 v0, s3, v79
	v_add_u32_e32 v4, s3, v80
	v_add_u32_e32 v8, s3, v81
	v_add_u32_e32 v12, s3, v82
	ds_read_b128 v[0:3], v0
	ds_read_b128 v[4:7], v4
	ds_read_b128 v[8:11], v8
	ds_read_b128 v[12:15], v12
	ds_read_b128 v[16:19], v44
	ds_read_b128 v[20:23], v44 offset:1024
	ds_read_b128 v[24:27], v44 offset:16384
	ds_read_b128 v[28:31], v44 offset:17408
	ds_read_b128 v[32:35], v44 offset:32768
	ds_read_b128 v[36:39], v44 offset:33792
	ds_read_b128 v[40:43], v44 offset:49152
	ds_read_b128 v[44:47], v44 offset:50176
	s_waitcnt lgkmcnt(5)
	v_pk_add_f32 v[18:19], v[18:19], v[26:27]
	v_pk_add_f32 v[16:17], v[16:17], v[24:25]
	s_waitcnt lgkmcnt(3)
	v_pk_add_f32 v[18:19], v[18:19], v[34:35]
	v_pk_add_f32 v[16:17], v[16:17], v[32:33]
	s_waitcnt lgkmcnt(1)
	v_pk_add_f32 v[18:19], v[18:19], v[42:43]
	v_pk_add_f32 v[16:17], v[16:17], v[40:41]
	v_pk_add_f32 v[2:3], v[18:19], v[2:3]
	v_pk_add_f32 v[0:1], v[16:17], v[0:1]
	v_pk_add_f32 v[2:3], v[2:3], v[6:7]
	v_pk_add_f32 v[0:1], v[0:1], v[4:5]
	v_pk_add_f32 v[2:3], v[2:3], v[10:11]
	v_pk_add_f32 v[0:1], v[0:1], v[8:9]
	s_lshl_b32 s0, s24, 7
	v_pk_add_f32 v[2:3], v[2:3], v[14:15]
	v_pk_add_f32 v[0:1], v[0:1], v[12:13]
	s_sub_i32 s0, s23, s0
	v_max_f32_e32 v0, 0, v0
	v_max_f32_e32 v1, 0, v1
	v_max_f32_e32 v2, 0, v2
	v_max_f32_e32 v3, 0, v3
	v_lshl_or_b32 v48, s0, 5, v78
	v_pk_mul_f32 v[0:1], v[0:1], v[0:1]
	v_pk_mul_f32 v[2:3], v[2:3], v[2:3]
	v_ashrrev_i32_e32 v49, 31, v48
	v_lshl_add_u64 v[48:49], v[48:49], 1, v[66:67]
	v_add_u32_e32 v8, s4, v81
	v_add_u32_e32 v12, s4, v82
	v_pk_add_f32 v[16:17], v[22:23], v[30:31]
	v_pk_add_f32 v[18:19], v[20:21], v[28:29]
	v_pk_add_f32 v[16:17], v[16:17], v[38:39]
	v_pk_add_f32 v[18:19], v[18:19], v[36:37]
	s_waitcnt lgkmcnt(0)
	v_pk_add_f32 v[16:17], v[16:17], v[46:47]
	v_pk_add_f32 v[18:19], v[18:19], v[44:45]
	s_add_i32 s23, s23, s70
	s_cmpk_gt_i32 s23, 0x7f
	s_waitcnt vmcnt(0)
	v_mul_f32_e32 v4, v50, v50
	v_pk_mul_f32 v[0:1], v[4:5], v[0:1] op_sel_hi:[0,1]
	v_pk_mul_f32 v[2:3], v[4:5], v[2:3] op_sel_hi:[0,1]
	v_cvt_pk_bf16_f32 v0, v0, v1
	v_cvt_pk_bf16_f32 v1, v2, v3
	global_store_dwordx2 v[48:49], v[0:1], off
	global_load_dword v24, v[64:65], off
	v_add_u32_e32 v0, s4, v79
	v_add_u32_e32 v4, s4, v80
	ds_read_b128 v[0:3], v0
	ds_read_b128 v[4:7], v4
	ds_read_b128 v[8:11], v8
	ds_read_b128 v[12:15], v12
	s_waitcnt lgkmcnt(3)
	v_pk_add_f32 v[2:3], v[16:17], v[2:3]
	v_pk_add_f32 v[0:1], v[18:19], v[0:1]
	s_waitcnt lgkmcnt(2)
	v_pk_add_f32 v[2:3], v[2:3], v[6:7]
	v_pk_add_f32 v[0:1], v[0:1], v[4:5]
	s_waitcnt lgkmcnt(1)
	v_pk_add_f32 v[2:3], v[2:3], v[10:11]
	v_pk_add_f32 v[0:1], v[0:1], v[8:9]
	s_waitcnt lgkmcnt(0)
	v_pk_add_f32 v[2:3], v[2:3], v[14:15]
	v_pk_add_f32 v[0:1], v[0:1], v[12:13]
	v_max_f32_e32 v2, 0, v2
	v_max_f32_e32 v0, 0, v0
	v_max_f32_e32 v1, 0, v1
	v_max_f32_e32 v3, 0, v3
	v_pk_mul_f32 v[0:1], v[0:1], v[0:1]
	v_pk_mul_f32 v[2:3], v[2:3], v[2:3]
	s_waitcnt vmcnt(0)
	v_mul_f32_e32 v4, v24, v24
	v_pk_mul_f32 v[0:1], v[4:5], v[0:1] op_sel_hi:[0,1]
	v_pk_mul_f32 v[2:3], v[4:5], v[2:3] op_sel_hi:[0,1]
	v_cvt_pk_bf16_f32 v0, v0, v1
	v_cvt_pk_bf16_f32 v1, v2, v3
	global_store_dwordx2 v[48:49], v[0:1], off offset:32
	s_cbranch_scc0 .LBB0_521

.LBB0_580:
	v_lshl_add_u64 v[82:83], v[70:71], 0, s[2:3]
	v_add_co_u32_e32 v98, vcc, s9, v82
	v_lshl_add_u64 v[126:127], v[72:73], 0, s[2:3]
	s_nop 1
	v_addc_co_u32_e32 v99, vcc, 0, v83, vcc
	v_add_co_u32_e32 v106, vcc, s10, v82
	s_add_u32 s2, s2, 0x80
	s_nop 1
	v_addc_co_u32_e32 v107, vcc, 0, v83, vcc
	v_add_co_u32_e32 v100, vcc, s11, v126
	s_addc_u32 s3, s3, 0
	s_nop 1
	v_addc_co_u32_e32 v101, vcc, 0, v127, vcc
	v_add_co_u32_e32 v110, vcc, s18, v126
	s_cmpk_eq_i32 s2, 0x100
	s_nop 1
	v_addc_co_u32_e32 v111, vcc, 0, v127, vcc
	v_add_co_u32_e32 v114, vcc, s19, v126
	s_nop 1
	v_addc_co_u32_e32 v115, vcc, 0, v127, vcc
	v_add_co_u32_e32 v118, vcc, s20, v126
	s_nop 1
	v_addc_co_u32_e32 v119, vcc, 0, v127, vcc
	v_add_co_u32_e32 v120, vcc, s21, v126
	s_nop 1
	v_addc_co_u32_e32 v121, vcc, 0, v127, vcc
	v_add_co_u32_e32 v122, vcc, s22, v126
	s_nop 1
	v_addc_co_u32_e32 v123, vcc, 0, v127, vcc
	v_add_co_u32_e32 v128, vcc, s23, v126
	s_nop 1
	v_addc_co_u32_e32 v129, vcc, 0, v127, vcc
	v_add_co_u32_e32 v134, vcc, s25, v126
	s_nop 1
	v_addc_co_u32_e32 v135, vcc, 0, v127, vcc
	global_load_dwordx4 v[82:85], v[98:99], off
	global_load_dwordx4 v[86:89], v[100:101], off
	global_load_dwordx4 v[90:93], v[98:99], off offset:64
	global_load_dwordx4 v[94:97], v[100:101], off offset:64
	global_load_dwordx4 v[98:101], v[106:107], off
	global_load_dwordx4 v[102:105], v[106:107], off offset:64
	global_load_dwordx4 v[188:191], v[110:111], off
	global_load_dwordx4 v[106:109], v[110:111], off offset:64
	global_load_dwordx4 v[222:225], v[114:115], off
	global_load_dwordx4 v[110:113], v[114:115], off offset:64
	global_load_dwordx4 v[230:233], v[118:119], off
	global_load_dwordx4 v[114:117], v[118:119], off offset:64
	global_load_dwordx4 v[234:237], v[120:121], off
	global_load_dwordx4 v[118:121], v[120:121], off offset:64
	global_load_dwordx4 v[238:241], v[122:123], off
	global_load_dwordx4 v[122:125], v[122:123], off offset:64
	global_load_dwordx4 v[242:245], v[128:129], off
	global_load_dwordx4 v[126:129], v[128:129], off offset:64
	global_load_dwordx4 v[130:133], v[134:135], off
	global_load_dwordx4 v[246:249], v[134:135], off offset:64
	v_lshl_add_u64 v[182:183], v[70:71], 0, s[2:3]
	v_lshl_add_u64 v[218:219], v[72:73], 0, s[2:3]
	s_add_u32 s2, s2, 0x80
	s_addc_u32 s3, s3, 0
	s_cmpk_eq_i32 s2, 0x100
	v_add_co_u32_e32 v200, vcc, s9, v182
	s_nop 1
	v_addc_co_u32_e32 v201, vcc, 0, v183, vcc
	global_load_dwordx4 v[192:195], v[200:201], off
	global_load_dwordx4 v[200:203], v[200:201], off offset:64
	v_add_co_u32_e32 v250, vcc, s10, v182
	s_nop 1
	v_addc_co_u32_e32 v251, vcc, 0, v183, vcc
	global_load_dwordx4 v[208:211], v[250:251], off
	global_load_dwordx4 v[250:253], v[250:251], off offset:64
	s_waitcnt vmcnt(22)
	v_mfma_f32_16x16x32_bf16 v[56:59], v[82:85], v[86:89], v[56:59]
	s_waitcnt vmcnt(19)
	v_mfma_f32_16x16x32_bf16 v[52:55], v[98:101], v[86:89], v[52:55]
	v_mfma_f32_16x16x32_bf16 v[56:59], v[90:93], v[94:97], v[56:59]
	s_waitcnt vmcnt(18)
	v_mfma_f32_16x16x32_bf16 v[52:55], v[102:105], v[94:97], v[52:55]
	v_add_co_u32_e32 v94, vcc, s11, v218
	s_nop 1
	v_addc_co_u32_e32 v95, vcc, 0, v219, vcc
	global_load_dwordx4 v[86:89], v[94:95], off
	global_load_dwordx4 v[94:97], v[94:95], off offset:64
	s_waitcnt vmcnt(19)
	v_mfma_f32_16x16x32_bf16 v[44:47], v[82:85], v[188:191], v[44:47]
	v_mfma_f32_16x16x32_bf16 v[20:23], v[98:101], v[188:191], v[20:23]
	s_waitcnt vmcnt(18)
	v_mfma_f32_16x16x32_bf16 v[44:47], v[90:93], v[106:109], v[44:47]
	v_mfma_f32_16x16x32_bf16 v[20:23], v[102:105], v[106:109], v[20:23]
	v_add_co_u32_e32 v106, vcc, s18, v218
	s_nop 1
	v_addc_co_u32_e32 v107, vcc, 0, v219, vcc
	global_load_dwordx4 v[188:191], v[106:107], off
	global_load_dwordx4 v[106:109], v[106:107], off offset:64
	s_waitcnt vmcnt(19)
	v_mfma_f32_16x16x32_bf16 v[12:15], v[82:85], v[222:225], v[12:15]
	v_mfma_f32_16x16x32_bf16 v[8:11], v[98:101], v[222:225], v[8:11]
	s_waitcnt vmcnt(18)
	v_mfma_f32_16x16x32_bf16 v[12:15], v[90:93], v[110:113], v[12:15]
	v_mfma_f32_16x16x32_bf16 v[8:11], v[102:105], v[110:113], v[8:11]
	v_add_co_u32_e32 v110, vcc, s19, v218
	s_nop 1
	v_addc_co_u32_e32 v111, vcc, 0, v219, vcc
	global_load_dwordx4 v[222:225], v[110:111], off
	global_load_dwordx4 v[110:113], v[110:111], off offset:64
	s_waitcnt vmcnt(19)
	v_mfma_f32_16x16x32_bf16 v[4:7], v[82:85], v[230:233], v[4:7]
	v_mfma_f32_16x16x32_bf16 v[0:3], v[98:101], v[230:233], v[0:3]
	s_waitcnt vmcnt(18)
	v_mfma_f32_16x16x32_bf16 v[4:7], v[90:93], v[114:117], v[4:7]
	v_mfma_f32_16x16x32_bf16 v[0:3], v[102:105], v[114:117], v[0:3]
	v_add_co_u32_e32 v114, vcc, s20, v218
	s_nop 1
	v_addc_co_u32_e32 v115, vcc, 0, v219, vcc
	global_load_dwordx4 v[230:233], v[114:115], off
	global_load_dwordx4 v[114:117], v[114:115], off offset:64
	s_waitcnt vmcnt(19)
	v_mfma_f32_16x16x32_bf16 v[16:19], v[82:85], v[234:237], v[16:19]
	v_mfma_f32_16x16x32_bf16 v[24:27], v[98:101], v[234:237], v[24:27]
	s_waitcnt vmcnt(18)
	v_mfma_f32_16x16x32_bf16 v[16:19], v[90:93], v[118:121], v[16:19]
	v_mfma_f32_16x16x32_bf16 v[24:27], v[102:105], v[118:121], v[24:27]
	v_add_co_u32_e32 v118, vcc, s21, v218
	s_nop 1
	v_addc_co_u32_e32 v119, vcc, 0, v219, vcc
	global_load_dwordx4 v[234:237], v[118:119], off
	global_load_dwordx4 v[118:121], v[118:119], off offset:64
	s_waitcnt vmcnt(19)
	v_mfma_f32_16x16x32_bf16 v[28:31], v[82:85], v[238:241], v[28:31]
	v_mfma_f32_16x16x32_bf16 v[32:35], v[98:101], v[238:241], v[32:35]
	s_waitcnt vmcnt(18)
	v_mfma_f32_16x16x32_bf16 v[28:31], v[90:93], v[122:125], v[28:31]
	v_mfma_f32_16x16x32_bf16 v[32:35], v[102:105], v[122:125], v[32:35]
	v_add_co_u32_e32 v122, vcc, s22, v218
	s_nop 1
	v_addc_co_u32_e32 v123, vcc, 0, v219, vcc
	global_load_dwordx4 v[238:241], v[122:123], off
	global_load_dwordx4 v[122:125], v[122:123], off offset:64
	s_waitcnt vmcnt(19)
	v_mfma_f32_16x16x32_bf16 v[36:39], v[82:85], v[242:245], v[36:39]
	v_mfma_f32_16x16x32_bf16 v[40:43], v[98:101], v[242:245], v[40:43]
	s_waitcnt vmcnt(17)
	v_mfma_f32_16x16x32_bf16 v[48:51], v[82:85], v[130:133], v[48:51]
	v_mfma_f32_16x16x32_bf16 v[60:63], v[98:101], v[130:133], v[60:63]
	v_mfma_f32_16x16x32_bf16 v[36:39], v[90:93], v[126:129], v[36:39]
	v_mfma_f32_16x16x32_bf16 v[40:43], v[102:105], v[126:129], v[40:43]
	v_add_co_u32_e32 v126, vcc, s23, v218
	s_nop 1
	v_addc_co_u32_e32 v127, vcc, 0, v219, vcc
	global_load_dwordx4 v[242:245], v[126:127], off
	global_load_dwordx4 v[126:129], v[126:127], off offset:64
	s_waitcnt vmcnt(18)
	v_mfma_f32_16x16x32_bf16 v[48:51], v[90:93], v[246:249], v[48:51]
	v_mfma_f32_16x16x32_bf16 v[60:63], v[102:105], v[246:249], v[60:63]
	v_add_co_u32_e32 v246, vcc, s25, v218
	s_nop 1
	v_addc_co_u32_e32 v247, vcc, 0, v219, vcc
	global_load_dwordx4 v[130:133], v[246:247], off
	global_load_dwordx4 v[246:249], v[246:247], off offset:64
	s_waitcnt vmcnt(15)
	v_mfma_f32_16x16x32_bf16 v[56:59], v[192:195], v[86:89], v[56:59]
	v_mfma_f32_16x16x32_bf16 v[52:55], v[208:211], v[86:89], v[52:55]
	s_waitcnt vmcnt(14)
	v_mfma_f32_16x16x32_bf16 v[56:59], v[200:203], v[94:97], v[56:59]
	v_mfma_f32_16x16x32_bf16 v[52:55], v[250:253], v[94:97], v[52:55]
	s_waitcnt vmcnt(13)
	v_mfma_f32_16x16x32_bf16 v[44:47], v[192:195], v[188:191], v[44:47]
	v_mfma_f32_16x16x32_bf16 v[20:23], v[208:211], v[188:191], v[20:23]
	s_waitcnt vmcnt(12)
	v_mfma_f32_16x16x32_bf16 v[44:47], v[200:203], v[106:109], v[44:47]
	v_mfma_f32_16x16x32_bf16 v[20:23], v[250:253], v[106:109], v[20:23]
	s_waitcnt vmcnt(11)
	v_mfma_f32_16x16x32_bf16 v[12:15], v[192:195], v[222:225], v[12:15]
	v_mfma_f32_16x16x32_bf16 v[8:11], v[208:211], v[222:225], v[8:11]
	s_waitcnt vmcnt(10)
	v_mfma_f32_16x16x32_bf16 v[12:15], v[200:203], v[110:113], v[12:15]
	v_mfma_f32_16x16x32_bf16 v[8:11], v[250:253], v[110:113], v[8:11]
	s_waitcnt vmcnt(9)
	v_mfma_f32_16x16x32_bf16 v[4:7], v[192:195], v[230:233], v[4:7]
	v_mfma_f32_16x16x32_bf16 v[0:3], v[208:211], v[230:233], v[0:3]
	s_waitcnt vmcnt(8)
	v_mfma_f32_16x16x32_bf16 v[4:7], v[200:203], v[114:117], v[4:7]
	v_mfma_f32_16x16x32_bf16 v[0:3], v[250:253], v[114:117], v[0:3]
	s_waitcnt vmcnt(7)
	v_mfma_f32_16x16x32_bf16 v[16:19], v[192:195], v[234:237], v[16:19]
	v_mfma_f32_16x16x32_bf16 v[24:27], v[208:211], v[234:237], v[24:27]
	s_waitcnt vmcnt(6)
	v_mfma_f32_16x16x32_bf16 v[16:19], v[200:203], v[118:121], v[16:19]
	v_mfma_f32_16x16x32_bf16 v[24:27], v[250:253], v[118:121], v[24:27]
	s_waitcnt vmcnt(5)
	v_mfma_f32_16x16x32_bf16 v[28:31], v[192:195], v[238:241], v[28:31]
	v_mfma_f32_16x16x32_bf16 v[32:35], v[208:211], v[238:241], v[32:35]
	s_waitcnt vmcnt(4)
	v_mfma_f32_16x16x32_bf16 v[28:31], v[200:203], v[122:125], v[28:31]
	v_mfma_f32_16x16x32_bf16 v[32:35], v[250:253], v[122:125], v[32:35]
	s_waitcnt vmcnt(3)
	v_mfma_f32_16x16x32_bf16 v[36:39], v[192:195], v[242:245], v[36:39]
	v_mfma_f32_16x16x32_bf16 v[40:43], v[208:211], v[242:245], v[40:43]
	s_waitcnt vmcnt(1)
	v_mfma_f32_16x16x32_bf16 v[48:51], v[192:195], v[130:133], v[48:51]
	v_mfma_f32_16x16x32_bf16 v[60:63], v[208:211], v[130:133], v[60:63]
	v_mfma_f32_16x16x32_bf16 v[36:39], v[200:203], v[126:129], v[36:39]
	v_mfma_f32_16x16x32_bf16 v[40:43], v[250:253], v[126:129], v[40:43]
	s_waitcnt vmcnt(0)
	v_mfma_f32_16x16x32_bf16 v[48:51], v[200:203], v[246:249], v[48:51]
	v_mfma_f32_16x16x32_bf16 v[60:63], v[250:253], v[246:249], v[60:63]
	v_add_u32_e32 v66, s6, v75
	s_waitcnt lgkmcnt(0)
	s_barrier
	ds_write_b128 v66, v[56:59]
	ds_write_b128 v66, v[52:55] offset:1024
	ds_write_b128 v66, v[44:47] offset:2048
	ds_write_b128 v66, v[20:23] offset:3072
	ds_write_b128 v66, v[12:15] offset:4096
	ds_write_b128 v66, v[8:11] offset:5120
	ds_write_b128 v66, v[4:7] offset:6144
	ds_write_b128 v66, v[0:3] offset:7168
	ds_write_b128 v66, v[16:19] offset:8192
	ds_write_b128 v66, v[24:27] offset:9216
	ds_write_b128 v66, v[28:31] offset:10240
	ds_write_b128 v66, v[32:35] offset:11264
	ds_write_b128 v66, v[36:39] offset:12288
	ds_write_b128 v66, v[40:43] offset:13312
	ds_write_b128 v66, v[48:51] offset:14336
	ds_write_b128 v66, v[60:63] offset:15360
	s_waitcnt lgkmcnt(0)
	s_barrier
	v_add_u32_e32 v22, s7, v75
	ds_read_b128 v[0:3], v22
	ds_read_b128 v[4:7], v22 offset:16384
	ds_read_b128 v[8:11], v22 offset:32768
	ds_read_b128 v[12:15], v22 offset:1024
	ds_read_b128 v[16:19], v22 offset:17408
	s_lshl_b32 s1, s0, 5
	s_sub_i32 s1, s5, s1
	v_lshl_or_b32 v28, s1, 5, v76
	s_waitcnt lgkmcnt(3)
	v_pk_add_f32 v[6:7], v[2:3], v[6:7]
	v_pk_add_f32 v[20:21], v[0:1], v[4:5]
	ds_read_b128 v[0:3], v22 offset:33792
	s_waitcnt lgkmcnt(3)
	v_pk_add_f32 v[24:25], v[6:7], v[10:11]
	ds_read_b128 v[4:7], v22 offset:49152
	v_pk_add_f32 v[26:27], v[20:21], v[8:9]
	v_add_u32_e32 v8, s7, v77
	ds_read_b128 v[8:11], v8
	ds_read_b128 v[20:23], v22 offset:50176
	s_ashr_i32 s1, s0, 31
	s_waitcnt lgkmcnt(2)
	v_pk_add_f32 v[26:27], v[26:27], v[4:5]
	v_add_u32_e32 v4, s7, v78
	v_pk_add_f32 v[24:25], v[24:25], v[6:7]
	ds_read_b128 v[4:7], v4
	s_waitcnt lgkmcnt(2)
	v_pk_add_f32 v[34:35], v[26:27], v[8:9]
	v_add_u32_e32 v8, s7, v79
	v_pk_add_f32 v[32:33], v[24:25], v[10:11]
	ds_read_b128 v[8:11], v8
	v_add_u32_e32 v24, s7, v80
	ds_read_b128 v[24:27], v24
	s_lshl_b64 s[0:1], s[0:1], 19
	s_waitcnt lgkmcnt(2)
	v_pk_add_f32 v[6:7], v[32:33], v[6:7]
	v_pk_add_f32 v[4:5], v[34:35], v[4:5]
	v_lshl_add_u64 v[30:31], v[64:65], 0, s[0:1]
	s_waitcnt lgkmcnt(1)
	v_pk_add_f32 v[6:7], v[6:7], v[10:11]
	v_pk_add_f32 v[4:5], v[4:5], v[8:9]
	v_ashrrev_i32_e32 v29, 31, v28
	s_waitcnt lgkmcnt(0)
	v_pk_add_f32 v[6:7], v[6:7], v[26:27]
	v_pk_add_f32 v[4:5], v[4:5], v[24:25]
	v_lshl_add_u64 v[24:25], v[28:29], 2, v[30:31]
	global_store_dwordx4 v[24:25], v[4:7], off
	s_add_i32 s5, s5, s4
	s_cmpk_gt_i32 s5, 0x7f
	v_pk_add_f32 v[6:7], v[12:13], v[16:17]
	v_pk_add_f32 v[4:5], v[14:15], v[18:19]
	v_pk_add_f32 v[6:7], v[6:7], v[0:1]
	v_add_u32_e32 v0, s8, v77
	v_pk_add_f32 v[4:5], v[4:5], v[2:3]
	ds_read_b128 v[0:3], v0
	v_pk_add_f32 v[8:9], v[4:5], v[22:23]
	v_pk_add_f32 v[10:11], v[6:7], v[20:21]
	v_add_u32_e32 v4, s8, v78
	ds_read_b128 v[4:7], v4
	s_waitcnt lgkmcnt(1)
	v_pk_add_f32 v[14:15], v[10:11], v[0:1]
	v_add_u32_e32 v0, s8, v79
	v_pk_add_f32 v[12:13], v[8:9], v[2:3]
	ds_read_b128 v[0:3], v0
	v_add_u32_e32 v8, s8, v80
	ds_read_b128 v[8:11], v8
	s_waitcnt lgkmcnt(2)
	v_pk_add_f32 v[6:7], v[12:13], v[6:7]
	v_pk_add_f32 v[4:5], v[14:15], v[4:5]
	s_waitcnt lgkmcnt(1)
	v_pk_add_f32 v[2:3], v[6:7], v[2:3]
	v_pk_add_f32 v[0:1], v[4:5], v[0:1]
	s_waitcnt lgkmcnt(0)
	v_pk_add_f32 v[2:3], v[2:3], v[10:11]
	v_pk_add_f32 v[0:1], v[0:1], v[8:9]
	global_store_dwordx4 v[24:25], v[0:3], off offset:64
	s_cbranch_scc0 .LBB0_579
